# P1 norm0 row loop: touch-prefetch of the x row two iterations ahead (4 dword loads, clamped row) on top of the batched parameter loads
# baseline (speedup 1.0000x reference)
.LBB0_663:
	v_add_u32_e32 v74, s6, v28
	v_min_i32_e32 v56, 0x8000, v28
	v_cmp_gt_i32_e32 vcc, s3, v74
	s_waitcnt vmcnt(0)
	v_pk_mul_f32 v[40:41], v[2:3], v[2:3]
	v_pk_mul_f32 v[42:43], v[6:7], v[6:7]
	v_pk_mul_f32 v[44:45], v[0:1], v[0:1]
	v_pk_mul_f32 v[46:47], v[4:5], v[4:5]
	v_pk_mul_f32 v[48:49], v[14:15], v[14:15]
	v_pk_mul_f32 v[50:51], v[10:11], v[10:11]
	v_pk_mul_f32 v[52:53], v[12:13], v[12:13]
	v_pk_mul_f32 v[54:55], v[8:9], v[8:9]
	v_cndmask_b32_e32 v28, v28, v74, vcc
	v_ashrrev_i32_e32 v60, 12, v56
	v_mov_b32_e32 v56, v52
	v_mov_b32_e32 v57, v54
	v_mov_b32_e32 v54, v53
	v_mov_b32_e32 v52, v48
	v_mov_b32_e32 v53, v50
	v_mov_b32_e32 v50, v49
	v_mov_b32_e32 v48, v44
	v_mov_b32_e32 v49, v46
	v_mov_b32_e32 v46, v45
	v_mov_b32_e32 v44, v40
	v_mov_b32_e32 v45, v42
	v_mov_b32_e32 v42, v41
	v_add_u32_e32 v41, 0xffff8000, v28
	v_mul_i32_i24_e32 v40, 0xc00, v60
	v_cmp_gt_i32_e32 vcc, s14, v28
	v_pk_add_f32 v[46:47], v[48:49], v[46:47]
	global_load_dwordx4 v[36:39], v[18:19], off
	global_load_dwordx4 v[140:143], v[18:19], off offset:1024
	global_load_dwordx4 v[144:147], v[18:19], off offset:2048
	global_load_dwordx4 v[148:151], v[18:19], off offset:3072
	v_cndmask_b32_e32 v48, v41, v28, vcc
	v_ashrrev_i32_e32 v41, 31, v40
	v_lshl_add_u64 v[40:41], v[40:41], 2, s[4:5]
	v_pk_add_f32 v[44:45], v[44:45], v[46:47]
	v_lshl_add_u64 v[66:67], v[40:41], 0, s[12:13]
	v_pk_add_f32 v[64:65], v[42:43], v[44:45]
	v_lshl_add_u64 v[68:69], v[40:41], 0, v[16:17]
	v_lshl_add_u64 v[44:45], v[66:67], 0, v[16:17]
	global_load_dwordx4 v[40:43], v[68:69], off
	global_load_dwordx4 v[152:155], v[68:69], off offset:1024
	global_load_dwordx4 v[156:159], v[68:69], off offset:2048
	global_load_dwordx4 v[160:163], v[68:69], off offset:3072
	s_nop 0
	global_load_dwordx4 v[164:167], v[44:45], off offset:1024
	global_load_dwordx4 v[168:171], v[44:45], off offset:2048
	global_load_dwordx4 v[172:175], v[44:45], off offset:3072
	global_load_dwordx4 v[44:47], v[44:45], off
	v_pk_add_f32 v[54:55], v[56:57], v[54:55]
	v_mov_b32_e32 v25, s57
	v_pk_add_f32 v[52:53], v[52:53], v[54:55]
	v_mov_b32_e32 v27, s53
	v_pk_add_f32 v[50:51], v[50:51], v[52:53]
	v_cndmask_b32_e32 v57, v25, v27, vcc
	v_add_f32_e32 v25, v50, v51
	v_mov_b32_e32 v23, v17
	v_add_f32_e32 v25, v65, v25
	v_lshl_add_u64 v[72:73], v[66:67], 0, v[22:23]
	v_add_f32_e32 v23, v64, v25
	ds_bpermute_b32 v25, v30, v23
	v_mov_b32_e32 v58, s56
	v_mov_b32_e32 v59, s52
	v_ashrrev_i32_e32 v61, 31, v28
	v_cndmask_b32_e32 v49, 0, v61, vcc
	s_waitcnt lgkmcnt(0)
	v_add_f32_e32 v23, v23, v25
	ds_bpermute_b32 v25, v31, v23
	v_cndmask_b32_e32 v56, v58, v59, vcc
	v_lshlrev_b64 v[48:49], 12, v[48:49]
	v_lshl_add_u64 v[48:49], v[56:57], 0, v[48:49]
	v_lshl_add_u64 v[70:71], v[48:49], 0, v[16:17]
	s_waitcnt lgkmcnt(0)
	v_add_f32_e32 v23, v23, v25
	ds_bpermute_b32 v25, v32, v23
	global_load_dwordx4 v[48:51], v[70:71], off
	global_load_dwordx4 v[52:55], v[70:71], off offset:1024
	global_load_dwordx4 v[56:59], v[70:71], off offset:2048
	global_load_dwordx4 v[60:63], v[70:71], off offset:3072
	v_add_u32_e32 v178, s6, v74
	v_cmp_gt_i32_e64 s[100:101], s14, v178
	v_mov_b32_e32 v179, 0
	s_nop 1
	v_cndmask_b32_e64 v178, 0, v178, s[100:101]
	v_lshlrev_b64 v[178:179], 12, v[178:179]
	v_lshl_add_u64 v[178:179], s[52:53], 0, v[178:179]
	v_lshl_add_u64 v[178:179], v[178:179], 0, v[16:17]
	global_load_dword v180, v[178:179], off
	global_load_dword v180, v[178:179], off offset:1024
	global_load_dword v180, v[178:179], off offset:2048
	global_load_dword v180, v[178:179], off offset:3072
	v_mov_b32_e32 v27, v17
	v_mov_b32_e32 v28, v74
	s_waitcnt lgkmcnt(0)
	v_add_f32_e32 v23, v23, v25
	ds_bpermute_b32 v25, v33, v23
	s_waitcnt lgkmcnt(0)
	v_add_f32_e32 v23, v23, v25
	ds_bpermute_b32 v25, v34, v23
	s_waitcnt lgkmcnt(0)
	v_add_f32_e32 v23, v23, v25
	ds_bpermute_b32 v25, v35, v23
	s_waitcnt lgkmcnt(0)
	v_add_f32_e32 v23, v23, v25
	v_fmamk_f32 v23, v23, 0x3a800000, v29
	v_mul_f32_e32 v25, 0x4b800000, v23
	v_cmp_gt_f32_e32 vcc, s15, v23
	s_nop 1
	v_cndmask_b32_e32 v23, v23, v25, vcc
	v_rsq_f32_e32 v23, v23
	s_nop 0
	v_mul_f32_e32 v25, 0x45800000, v23
	v_cndmask_b32_e32 v64, v23, v25, vcc
	v_pk_mul_f32 v[12:13], v[12:13], v[64:65] op_sel_hi:[1,0]
	v_pk_mul_f32 v[14:15], v[14:15], v[64:65] op_sel_hi:[1,0]
	v_pk_mul_f32 v[8:9], v[8:9], v[64:65] op_sel_hi:[1,0]
	v_pk_mul_f32 v[10:11], v[10:11], v[64:65] op_sel_hi:[1,0]
	v_mov_b32_e32 v25, v17
	v_pk_mul_f32 v[4:5], v[4:5], v[64:65] op_sel_hi:[1,0]
	v_pk_mul_f32 v[6:7], v[6:7], v[64:65] op_sel_hi:[1,0]
	v_cmp_lt_i32_e32 vcc, s7, v74
	s_or_b64 s[10:11], vcc, s[10:11]
	s_waitcnt vmcnt(8)
	v_pk_mul_f32 v[12:13], v[36:37], v[12:13]
	v_pk_mul_f32 v[14:15], v[38:39], v[14:15]
	v_pk_add_f32 v[36:37], v[44:45], 1.0 op_sel_hi:[1,0]
	v_pk_add_f32 v[38:39], v[46:47], 1.0 op_sel_hi:[1,0]
	v_pk_fma_f32 v[12:13], v[36:37], v[12:13], v[40:41]
	v_pk_fma_f32 v[14:15], v[38:39], v[14:15], v[42:43]
	v_cvt_pk_bf16_f32 v12, v12, v13
	v_cvt_pk_bf16_f32 v13, v14, v15
	global_store_dwordx2 v[20:21], v[12:13], off
	s_nop 0
	v_lshl_add_u64 v[44:45], v[66:67], 0, v[24:25]
	v_lshl_add_u64 v[66:67], v[66:67], 0, v[26:27]
	v_pk_mul_f32 v[8:9], v[140:141], v[8:9]
	v_pk_add_f32 v[12:13], v[164:165], 1.0 op_sel_hi:[1, 0]
	v_pk_mul_f32 v[10:11], v[142:143], v[10:11]
	v_pk_add_f32 v[14:15], v[166:167], 1.0 op_sel_hi:[1, 0]
	v_pk_fma_f32 v[8:9], v[12:13], v[8:9], v[152:153]
	v_pk_fma_f32 v[10:11], v[14:15], v[10:11], v[154:155]
	v_cvt_pk_bf16_f32 v8, v8, v9
	v_cvt_pk_bf16_f32 v9, v10, v11
	global_store_dwordx2 v[20:21], v[8:9], off offset:512
	s_nop 0
	v_pk_mul_f32 v[4:5], v[144:145], v[4:5]
	v_pk_add_f32 v[8:9], v[168:169], 1.0 op_sel_hi:[1, 0]
	v_pk_mul_f32 v[6:7], v[146:147], v[6:7]
	v_pk_add_f32 v[10:11], v[170:171], 1.0 op_sel_hi:[1, 0]
	v_pk_fma_f32 v[4:5], v[4:5], v[8:9], v[156:157]
	v_pk_fma_f32 v[6:7], v[6:7], v[10:11], v[158:159]
	v_cvt_pk_bf16_f32 v4, v4, v5
	v_cvt_pk_bf16_f32 v5, v6, v7
	global_store_dwordx2 v[20:21], v[4:5], off offset:1024
	v_pk_mul_f32 v[66:67], v[0:1], v[64:65] op_sel_hi:[1,0]
	v_pk_mul_f32 v[64:65], v[2:3], v[64:65] op_sel_hi:[1,0]
	s_waitcnt vmcnt(7)
	v_mov_b32_e32 v12, v48
	v_mov_b32_e32 v13, v49
	v_mov_b32_e32 v14, v50
	v_mov_b32_e32 v15, v51
	v_mov_b32_e32 v8, v52
	v_mov_b32_e32 v9, v53
	v_mov_b32_e32 v10, v54
	v_mov_b32_e32 v11, v55
	v_mov_b32_e32 v4, v56
	v_mov_b32_e32 v5, v57
	v_mov_b32_e32 v6, v58
	v_mov_b32_e32 v7, v59
	v_mov_b32_e32 v0, v60
	v_mov_b32_e32 v1, v61
	v_mov_b32_e32 v2, v62
	v_mov_b32_e32 v3, v63
	v_pk_mul_f32 v[36:37], v[66:67], v[148:149]
	v_pk_add_f32 v[40:41], v[172:173], 1.0 op_sel_hi:[1, 0]
	v_pk_mul_f32 v[38:39], v[64:65], v[150:151]
	v_pk_add_f32 v[42:43], v[174:175], 1.0 op_sel_hi:[1, 0]
	v_pk_fma_f32 v[36:37], v[36:37], v[40:41], v[160:161]
	v_pk_fma_f32 v[38:39], v[38:39], v[42:43], v[162:163]
	v_cvt_pk_bf16_f32 v36, v36, v37
	v_cvt_pk_bf16_f32 v37, v38, v39
	global_store_dwordx2 v[20:21], v[36:37], off offset:1536
	v_lshl_add_u64 v[20:21], v[20:21], 0, s[8:9]
	s_andn2_b64 exec, exec, s[10:11]
	s_cbranch_execnz .LBB0_663
